# attention slc loop: far-tile fast path issues K fragment reads before the next tile's LDS-DMA (DMA issue overlaps LDS latency); on top of v22
# baseline (speedup 1.0000x reference)
.LBB0_1975:
	v_add_u32_e32 v0, 1, v68
	v_lshrrev_b64 v[66:67], v0, v[130:131]
	v_cmp_eq_u64_e64 s[6:7], 0, v[66:67]
	v_ffbl_b32_e32 v67, v67
	v_add_u32_e32 v67, 32, v67
	v_ffbl_b32_e32 v66, v66
	v_cmp_lt_u32_e32 vcc, 62, v68
	v_min_u32_e32 v66, v66, v67
	s_waitcnt vmcnt(0)
	v_add_u32_e32 v157, v0, v66
	s_or_b64 s[6:7], vcc, s[6:7]
	v_cndmask_b32_e64 v0, v157, -1, s[6:7]
	v_cmp_gt_i32_e64 s[6:7], 0, v0
	s_mov_b64 s[8:9], 0
	s_barrier
	v_readfirstlane_b32 s100, v68
	s_nop 3
	s_lshl_b32 s100, s100, 6
	s_sub_i32 s100, s54, s100
	s_cmpk_lt_i32 s100, 0x80
	s_cbranch_scc1 .Lslc_slow
	s_lshl_b32 s20, s53, 14
	s_add_i32 s62, s20, 0
	v_lshlrev_b32_e64 v82, v68, 1
	v_and_b32_e32 v82, v82, v154
	v_cmp_ne_u32_e64 s[44:45], 0, v82
	v_mov_b32_e32 v180, s52
	ds_read_b32 v180, v180 offset:512
	v_add_u32_e32 v66, s62, v137
	v_add_u32_e32 v74, v66, v138
	v_add_u32_e32 v75, v66, v140
	v_add_u32_e32 v76, v66, v141
	v_add_u32_e32 v77, v66, v142
	ds_read_b128 v[66:69], v74 offset:32768
	ds_read_b128 v[70:73], v74 offset:40960
	ds_read_b128 v[194:197], v75 offset:32768
	ds_read_b128 v[202:205], v75 offset:40960
	ds_read_b128 v[210:213], v76 offset:32768
	ds_read_b128 v[218:221], v76 offset:40960
	ds_read_b128 v[226:229], v77 offset:32768
	ds_read_b128 v[234:237], v77 offset:40960
	v_xor_b32_e32 v158, 0x80, v74
	ds_read_b128 v[158:161], v158 offset:32768
	v_xor_b32_e32 v164, 0x80, v74
	ds_read_b128 v[164:167], v164 offset:40960
	v_xor_b32_e32 v198, 0x80, v75
	ds_read_b128 v[198:201], v198 offset:32768
	v_xor_b32_e32 v206, 0x80, v75
	ds_read_b128 v[206:209], v206 offset:40960
	v_xor_b32_e32 v214, 0x80, v76
	ds_read_b128 v[214:217], v214 offset:32768
	v_xor_b32_e32 v222, 0x80, v76
	ds_read_b128 v[222:225], v222 offset:40960
	v_xor_b32_e32 v230, 0x80, v77
	ds_read_b128 v[230:233], v230 offset:32768
	v_xor_b32_e32 v238, 0x80, v77
	ds_read_b128 v[238:241], v238 offset:40960
	s_and_saveexec_b64 s[10:11], s[6:7]
	s_xor_b64 s[10:11], exec, s[10:11]
	s_cbranch_execz .Lsf_1980
	s_and_b64 vcc, exec, s[40:41]
	s_cbranch_vccz .Lsf_1978
	s_lshl_b32 s8, s53, 14
	s_xor_b32 s12, s8, 0x4000
	s_add_i32 s8, s47, s12
	s_add_i32 m0, s8, 0x8000
	s_nop 0
	global_load_lds_dwordx4 v[132:133], off
	s_add_i32 m0, s8, 0x8400
	s_mov_b64 s[8:9], -1
	global_load_lds_dwordx4 v[134:135], off
	s_branch .Lsf_1979

.Lsf_1980:
	s_or_saveexec_b64 s[10:11], s[10:11]
	v_mov_b64_e32 v[82:83], s[42:43]
	v_mov_b32_e32 v85, s12
	s_xor_b64 exec, exec, s[10:11]
	s_cbranch_execz .Lsf_1982
	s_lshl_b32 s12, s53, 14
	v_lshlrev_b64 v[82:83], 14, v[0:1]
	s_xor_b32 s12, s12, 0x4000
	v_lshl_add_u64 v[86:87], s[14:15], 0, v[82:83]
	s_add_i32 s13, s47, s12
	v_lshl_add_u64 v[88:89], v[86:87], 0, v[172:173]
	s_add_i32 m0, s13, 0x8000
	v_lshl_add_u64 v[86:87], v[86:87], 0, v[176:177]
	global_load_lds_dwordx4 v[88:89], off
	s_add_i32 m0, s13, 0x8400
	v_lshl_add_u64 v[82:83], s[16:17], 0, v[82:83]
	global_load_lds_dwordx4 v[86:87], off
	v_mov_b32_e32 v85, s12
	s_or_b64 s[8:9], s[8:9], exec
.Lsf_1982:
	s_or_b64 exec, exec, s[10:11]
	s_and_saveexec_b64 s[10:11], s[8:9]
	s_cbranch_execz .Lsf_1984
	v_add_u32_e32 v0, s47, v85
	v_lshl_add_u64 v[86:87], v[82:83], 0, v[174:175]
	v_readfirstlane_b32 s8, v0
	v_add_u32_e32 v0, 0x400, v0
	s_mov_b32 m0, s8
	v_readfirstlane_b32 s8, v0
	global_load_lds_dwordx4 v[86:87], off
	v_lshl_add_u64 v[82:83], v[82:83], 0, v[178:179]
	s_mov_b32 m0, s8
	s_nop 0
	global_load_lds_dwordx4 v[82:83], off
.Lsf_1984:
	s_or_b64 exec, exec, s[10:11]
	s_waitcnt lgkmcnt(8)
	v_mfma_f32_32x32x16_bf16 v[82:97], v[66:69], v[98:101], 0
	v_mfma_f32_32x32x16_bf16 v[66:81], v[70:73], v[98:101], 0
	v_mfma_f32_32x32x16_bf16 v[82:97], v[194:197], v[102:105], v[82:97]
	v_mfma_f32_32x32x16_bf16 v[66:81], v[202:205], v[102:105], v[66:81]
	v_mfma_f32_32x32x16_bf16 v[82:97], v[210:213], v[106:109], v[82:97]
	v_mfma_f32_32x32x16_bf16 v[66:81], v[218:221], v[106:109], v[66:81]
	v_mfma_f32_32x32x16_bf16 v[82:97], v[226:229], v[110:113], v[82:97]
	v_mfma_f32_32x32x16_bf16 v[66:81], v[234:237], v[110:113], v[66:81]
	s_waitcnt lgkmcnt(0)
	v_mfma_f32_32x32x16_bf16 v[82:97], v[158:161], v[114:117], v[82:97]
	v_mfma_f32_32x32x16_bf16 v[66:81], v[164:167], v[114:117], v[66:81]
	v_mfma_f32_32x32x16_bf16 v[82:97], v[198:201], v[118:121], v[82:97]
	v_mfma_f32_32x32x16_bf16 v[66:81], v[206:209], v[118:121], v[66:81]
	v_mfma_f32_32x32x16_bf16 v[82:97], v[214:217], v[122:125], v[82:97]
	v_mfma_f32_32x32x16_bf16 v[66:81], v[222:225], v[122:125], v[66:81]
	v_mfma_f32_32x32x16_bf16 v[82:97], v[230:233], v[126:129], v[82:97]
	v_mfma_f32_32x32x16_bf16 v[66:81], v[238:241], v[126:129], v[66:81]
	v_sub_f32_e32 v0, v180, v153
	v_cndmask_b32_e64 v0, v186, v0, s[44:45]
	s_mov_b64 s[10:11], exec
	s_branch .LBB0_1974
.Lslc_slow:
	s_and_saveexec_b64 s[10:11], s[6:7]
	s_xor_b64 s[10:11], exec, s[10:11]
	s_cbranch_execz .LBB0_1980
	s_and_b64 vcc, exec, s[40:41]
	s_cbranch_vccz .LBB0_1978
	s_lshl_b32 s8, s53, 14
	s_xor_b32 s12, s8, 0x4000
	s_add_i32 s8, s47, s12
	s_add_i32 m0, s8, 0x8000
	s_nop 0
	global_load_lds_dwordx4 v[132:133], off
	s_add_i32 m0, s8, 0x8400
	s_mov_b64 s[8:9], -1
	global_load_lds_dwordx4 v[134:135], off
	s_branch .LBB0_1979

	.amdhsa_kernel _Z3fwd4Args
		.amdhsa_group_segment_fixed_size 0
		.amdhsa_private_segment_fixed_size 0
		.amdhsa_kernarg_size 520
		.amdhsa_user_sgpr_count 2
		.amdhsa_user_sgpr_dispatch_ptr 0
		.amdhsa_user_sgpr_queue_ptr 0
		.amdhsa_user_sgpr_kernarg_segment_ptr 1
		.amdhsa_user_sgpr_dispatch_id 0
		.amdhsa_user_sgpr_kernarg_preload_length 0
		.amdhsa_user_sgpr_kernarg_preload_offset 0
		.amdhsa_user_sgpr_private_segment_size 0
		.amdhsa_uses_dynamic_stack 0
		.amdhsa_enable_private_segment 0
		.amdhsa_system_sgpr_workgroup_id_x 1
		.amdhsa_system_sgpr_workgroup_id_y 0
		.amdhsa_system_sgpr_workgroup_id_z 0
		.amdhsa_system_sgpr_workgroup_info 0
		.amdhsa_system_vgpr_workitem_id 0
		.amdhsa_next_free_vgpr 256
		.amdhsa_next_free_sgpr 101
		.amdhsa_accum_offset 256
		.amdhsa_reserve_vcc 1
		.amdhsa_float_round_mode_32 0
		.amdhsa_float_round_mode_16_64 0
		.amdhsa_float_denorm_mode_32 3
		.amdhsa_float_denorm_mode_16_64 3
		.amdhsa_dx10_clamp 1
		.amdhsa_ieee_mode 1
		.amdhsa_fp16_overflow 0
		.amdhsa_tg_split 0
		.amdhsa_exception_fp_ieee_invalid_op 0
		.amdhsa_exception_fp_denorm_src 0
		.amdhsa_exception_fp_ieee_div_zero 0
		.amdhsa_exception_fp_ieee_overflow 0
		.amdhsa_exception_fp_ieee_underflow 0
		.amdhsa_exception_fp_ieee_inexact 0
		.amdhsa_exception_int_div_zero 0
	.end_amdhsa_kernel

amdhsa.kernels:
  - .agpr_count:     0
    .args:
      - .offset:         0
        .size:           264
        .value_kind:     by_value
      - .offset:         264
        .size:           4
        .value_kind:     hidden_block_count_x
      - .offset:         268
        .size:           4
        .value_kind:     hidden_block_count_y
      - .offset:         272
        .size:           4
        .value_kind:     hidden_block_count_z
      - .offset:         276
        .size:           2
        .value_kind:     hidden_group_size_x
      - .offset:         278
        .size:           2
        .value_kind:     hidden_group_size_y
      - .offset:         280
        .size:           2
        .value_kind:     hidden_group_size_z
      - .offset:         282
        .size:           2
        .value_kind:     hidden_remainder_x
      - .offset:         284
        .size:           2
        .value_kind:     hidden_remainder_y
      - .offset:         286
        .size:           2
        .value_kind:     hidden_remainder_z
      - .offset:         304
        .size:           8
        .value_kind:     hidden_global_offset_x
      - .offset:         312
        .size:           8
        .value_kind:     hidden_global_offset_y
      - .offset:         320
        .size:           8
        .value_kind:     hidden_global_offset_z
      - .offset:         328
        .size:           2
        .value_kind:     hidden_grid_dims
      - .offset:         384
        .size:           4
        .value_kind:     hidden_dynamic_lds_size
    .group_segment_fixed_size: 0
    .kernarg_segment_align: 8
    .kernarg_segment_size: 520
    .language:       OpenCL C
    .language_version:
      - 2
      - 0
    .max_flat_workgroup_size: 512
    .name:           _Z3fwd4Args
    .private_segment_fixed_size: 0
    .sgpr_count:     107
    .sgpr_spill_count: 240
    .symbol:         _Z3fwd4Args.kd
    .uniform_work_group_size: 1
    .uses_dynamic_stack: false
    .vgpr_count:     256
    .vgpr_spill_count: 0
    .wavefront_size: 64
